# third-round half tiles: the two workgroups sharing a tile now sit on the same XCD (wg and wg+8) and the tile id keeps id%8 = XCD
# speedup vs baseline: 1.0005x; 1.0005x over previous
.LBB0_157:
	s_add_i32 s37, s37, 1
	s_mul_i32 s0, s37, s36
	s_mul_hi_u32 s1, s37, s33
	s_add_i32 s1, s1, s0
	s_mul_i32 s0, s37, s33
	v_readlane_b32 s11, v252, 0
	s_add_u32 s14, s0, s11
	v_readlane_b32 s0, v252, 10
	s_addc_u32 s15, s1, s0
	s_cmp_eq_u32 s37, 2
	s_cbranch_scc0 .Lq_full_B
	s_lshr_b32 s14, s11, 4
	s_lshl_b32 s14, s14, 3
	s_and_b32 s70, s11, 7
	s_or_b32 s14, s14, s70
	s_addk_i32 s14, 0x200
	s_mov_b32 s15, 0
	s_bfe_u32 s70, s11, 0x10003
	s_add_i32 s70, s70, 1
	s_branch .Lq_cont_B

.LBB0_506:
	s_add_i32 s81, s81, 1
	s_mul_i32 s15, s81, s80
	s_mul_hi_u32 s17, s81, s76
	s_add_i32 s17, s17, s15
	s_mul_i32 s15, s81, s76
	v_readlane_b32 s18, v252, 0
	s_add_u32 s18, s15, s18
	v_readlane_b32 s15, v252, 10
	s_addc_u32 s19, s17, s15
	s_cmp_eq_u32 s81, 2
	s_cbranch_scc0 .Lq_full_W
	v_readlane_b32 s15, v252, 0
	s_lshr_b32 s18, s15, 4
	s_lshl_b32 s18, s18, 3
	s_and_b32 s70, s15, 7
	s_or_b32 s18, s18, s70
	s_bfe_u32 s70, s15, 0x10003
	s_add_i32 s70, s70, 1
	s_addk_i32 s18, 0x200
	s_mov_b32 s19, 0
	s_branch .Lq_cont_W
